# hand-written mode-7 (gate quad) P1 epilogue: v_permlane16_swap exchange instead of ds_bpermute+cndmask, saddr stores
# speedup vs baseline: 1.0082x; 1.0082x over previous
;     __device__ __forceinline__ void operator()(f32x4 (&acc)[2][2][4][2], const Unit& u, int wr, int wc, int fr, int fq) const {
;     ...
;         if (mode == 7) {
;             const int row0q = u.pm * BM + wr * 64 + fr; const int ch = 64 * (pn - 32) + 16 * wc + 4 * fq;
; #pragma unroll
;             for (int ai = 0; ai < 2; ++ai)
; #pragma unroll
;                 for (int m = 0; m < 4; ++m) {
;                     bf16_t* rowp = O + (size_t)(row0q + ai * HALF + m * 16) * LDP + ch;
;                     float r0v[4], r1v[4], g2v[4], szv[4];
; #pragma unroll
;                     for (int j = 0; j < 4; ++j) {
;                         const float ea = fminf(__builtin_amdgcn_exp2f(-1.4426950409f * acc[ai][0][m][0][j]), 1e30f);
;                         const float eb = fminf(__builtin_amdgcn_exp2f(-1.4426950409f * acc[ai][0][m][1][j]), 1e30f);
;                         const float ec = fminf(__builtin_amdgcn_exp2f(-1.4426950409f * acc[ai][1][m][0][j]), 1e30f);
;                         const float xz = acc[ai][1][m][1][j];
;                         const float ia = __builtin_amdgcn_rcpf(1.0f + ea), ib = __builtin_amdgcn_rcpf(1.0f + eb), ic = __builtin_amdgcn_rcpf(1.0f + ec);
;                         r0v[j] = (1.0f + eb) * ia; r1v[j] = (1.0f + ec) * ib; g2v[j] = ic; szv[j] = xz * sigmoid_f(xz);
;                     }
;                     u32x2 wr0, wr1, wg2, wsz;
;                     wr0.x = cvt_pk_bf16(r0v[0], r0v[1]); wr0.y = cvt_pk_bf16(r0v[2], r0v[3]);
;                     wr1.x = cvt_pk_bf16(r1v[0], r1v[1]); wr1.y = cvt_pk_bf16(r1v[2], r1v[3]);
;                     wg2.x = cvt_pk_bf16(g2v[0], g2v[1]); wg2.y = cvt_pk_bf16(g2v[2], g2v[3]);
;                     wsz.x = cvt_pk_bf16(szv[0], szv[1]); wsz.y = cvt_pk_bf16(szv[2], szv[3]);
;                     const bool odd = (fq & 1) != 0;
;                     const u32x2 s0 = odd ? wr0 : wg2, s1 = odd ? wr1 : wsz;
;                     u32x2 q0, q1;
;                     q0.x = (unsigned)__shfl_xor((int)s0.x, 16); q0.y = (unsigned)__shfl_xor((int)s0.y, 16);
;                     q1.x = (unsigned)__shfl_xor((int)s1.x, 16); q1.y = (unsigned)__shfl_xor((int)s1.y, 16);
;                     u32x4 o0, o1;
;                     if (!odd) { o0 = (u32x4){wr0.x, wr0.y, q0.x, q0.y}; o1 = (u32x4){wr1.x, wr1.y, q1.x, q1.y}; }
.LBB0_424:
	v_mov_b32_e32 v184, 8
	v_cndmask_b32_e64 v184, v184, 0, s[38:39]
	v_lshlrev_b32_e32 v185, 11, v164
	v_add_u32_e32 v185, v185, v136
	v_sub_u32_e32 v185, v185, v184
	v_mov_b32_e32 v186, 0x20000000
	v_mov_b32_e32 v187, 0x14000000
	v_cndmask_b32_e64 v186, v186, v187, s[38:39]
	v_add_u32_e32 v150, v185, v186
	v_mov_b32_e32 v186, 0xc000000
	v_mov_b32_e32 v187, 0x1c000000
	v_cndmask_b32_e64 v186, v186, v187, s[38:39]
	v_add_u32_e32 v151, v185, v186
	s_lshl_b32 s14, s60, 19
	s_add_u32 s24, s70, s14
	s_addc_u32 s25, s71, 0
	s_lshl_b32 s14, s59, 7
	s_sub_u32 s14, s14, 0x1000
	s_add_u32 s24, s24, s14
	s_addc_u32 s25, s25, 0
	v_mul_f32_e32 v124, 0xbfb8aa3b, v124
	v_mul_f32_e32 v125, 0xbfb8aa3b, v125
	v_mul_f32_e32 v126, 0xbfb8aa3b, v126
	v_mul_f32_e32 v127, 0xbfb8aa3b, v127
	v_mul_f32_e32 v120, 0xbfb8aa3b, v120
	v_mul_f32_e32 v121, 0xbfb8aa3b, v121
	v_mul_f32_e32 v122, 0xbfb8aa3b, v122
	v_mul_f32_e32 v123, 0xbfb8aa3b, v123
	v_mul_f32_e32 v116, 0xbfb8aa3b, v116
	v_mul_f32_e32 v117, 0xbfb8aa3b, v117
	v_mul_f32_e32 v118, 0xbfb8aa3b, v118
	v_mul_f32_e32 v119, 0xbfb8aa3b, v119
	v_mul_f32_e32 v160, 0xbfb8aa3b, v112
	v_mul_f32_e32 v161, 0xbfb8aa3b, v113
	v_mul_f32_e32 v162, 0xbfb8aa3b, v114
	v_mul_f32_e32 v163, 0xbfb8aa3b, v115
	v_exp_f32_e32 v124, v124
	v_exp_f32_e32 v125, v125
	v_exp_f32_e32 v126, v126
	v_exp_f32_e32 v127, v127
	v_exp_f32_e32 v120, v120
	v_exp_f32_e32 v121, v121
	v_exp_f32_e32 v122, v122
	v_exp_f32_e32 v123, v123
	v_exp_f32_e32 v116, v116
	v_exp_f32_e32 v117, v117
	v_exp_f32_e32 v118, v118
	v_exp_f32_e32 v119, v119
	v_exp_f32_e32 v160, v160
	v_exp_f32_e32 v161, v161
	v_exp_f32_e32 v162, v162
	v_exp_f32_e32 v163, v163
	v_min_f32_e32 v124, 0x7149f2ca, v124
	v_min_f32_e32 v125, 0x7149f2ca, v125
	v_min_f32_e32 v126, 0x7149f2ca, v126
	v_min_f32_e32 v127, 0x7149f2ca, v127
	v_min_f32_e32 v120, 0x7149f2ca, v120
	v_min_f32_e32 v121, 0x7149f2ca, v121
	v_min_f32_e32 v122, 0x7149f2ca, v122
	v_min_f32_e32 v123, 0x7149f2ca, v123
	v_min_f32_e32 v116, 0x7149f2ca, v116
	v_min_f32_e32 v117, 0x7149f2ca, v117
	v_min_f32_e32 v118, 0x7149f2ca, v118
	v_min_f32_e32 v119, 0x7149f2ca, v119
	v_add_f32_e32 v124, 1.0, v124
	v_add_f32_e32 v125, 1.0, v125
	v_add_f32_e32 v126, 1.0, v126
	v_add_f32_e32 v127, 1.0, v127
	v_add_f32_e32 v120, 1.0, v120
	v_add_f32_e32 v121, 1.0, v121
	v_add_f32_e32 v122, 1.0, v122
	v_add_f32_e32 v123, 1.0, v123
	v_add_f32_e32 v116, 1.0, v116
	v_add_f32_e32 v117, 1.0, v117
	v_add_f32_e32 v118, 1.0, v118
	v_add_f32_e32 v119, 1.0, v119
	v_add_f32_e32 v160, 1.0, v160
	v_add_f32_e32 v161, 1.0, v161
	v_add_f32_e32 v162, 1.0, v162
	v_add_f32_e32 v163, 1.0, v163
	v_rcp_f32_e32 v152, v124
	v_rcp_f32_e32 v153, v125
	v_rcp_f32_e32 v154, v126
	v_rcp_f32_e32 v155, v127
	v_rcp_f32_e32 v156, v120
	v_rcp_f32_e32 v157, v121
	v_rcp_f32_e32 v158, v122
	v_rcp_f32_e32 v159, v123
	v_rcp_f32_e32 v160, v160
	v_rcp_f32_e32 v161, v161
	v_rcp_f32_e32 v162, v162
	v_rcp_f32_e32 v163, v163
	v_mul_f32_e32 v152, v120, v152
	v_mul_f32_e32 v153, v121, v153
	v_mul_f32_e32 v154, v122, v154
	v_mul_f32_e32 v155, v123, v155
	v_mul_f32_e32 v156, v116, v156
	v_mul_f32_e32 v157, v117, v157
	v_mul_f32_e32 v158, v118, v158
	v_mul_f32_e32 v159, v119, v159
	v_rcp_f32_e32 v116, v116
	v_rcp_f32_e32 v117, v117
	v_rcp_f32_e32 v118, v118
	v_rcp_f32_e32 v119, v119
	v_mul_f32_e32 v160, v112, v160
	v_mul_f32_e32 v161, v113, v161
	v_mul_f32_e32 v162, v114, v162
	v_mul_f32_e32 v163, v115, v163
	v_cvt_pk_bf16_f32 v168, v152, v153
	v_cvt_pk_bf16_f32 v169, v154, v155
	v_cvt_pk_bf16_f32 v172, v156, v157
	v_cvt_pk_bf16_f32 v173, v158, v159
	v_cvt_pk_bf16_f32 v174, v160, v161
	v_cvt_pk_bf16_f32 v175, v162, v163
	v_cvt_pk_bf16_f32 v170, v116, v117
	v_cvt_pk_bf16_f32 v171, v118, v119
	s_nop 1
	v_permlane16_swap_b32_e32 v172, v174
	v_permlane16_swap_b32_e32 v173, v175
	v_permlane16_swap_b32_e32 v168, v170
	v_permlane16_swap_b32_e32 v169, v171
	global_store_dwordx4 v151, v[172:175], s[24:25]
	global_store_dwordx4 v150, v[168:171], s[24:25]
	s_add_u32 s24, s24, 0x8000
	s_addc_u32 s25, s25, 0
	v_mul_f32_e32 v108, 0xbfb8aa3b, v108
	v_mul_f32_e32 v109, 0xbfb8aa3b, v109
	v_mul_f32_e32 v110, 0xbfb8aa3b, v110
	v_mul_f32_e32 v111, 0xbfb8aa3b, v111
	v_mul_f32_e32 v104, 0xbfb8aa3b, v104
	v_mul_f32_e32 v105, 0xbfb8aa3b, v105
	v_mul_f32_e32 v106, 0xbfb8aa3b, v106
	v_mul_f32_e32 v107, 0xbfb8aa3b, v107
	v_mul_f32_e32 v100, 0xbfb8aa3b, v100
	v_mul_f32_e32 v101, 0xbfb8aa3b, v101
	v_mul_f32_e32 v102, 0xbfb8aa3b, v102
	v_mul_f32_e32 v103, 0xbfb8aa3b, v103
	v_mul_f32_e32 v160, 0xbfb8aa3b, v96
	v_mul_f32_e32 v161, 0xbfb8aa3b, v97
	v_mul_f32_e32 v162, 0xbfb8aa3b, v98
	v_mul_f32_e32 v163, 0xbfb8aa3b, v99
	v_exp_f32_e32 v108, v108
	v_exp_f32_e32 v109, v109
	v_exp_f32_e32 v110, v110
	v_exp_f32_e32 v111, v111
	v_exp_f32_e32 v104, v104
	v_exp_f32_e32 v105, v105
	v_exp_f32_e32 v106, v106
	v_exp_f32_e32 v107, v107
	v_exp_f32_e32 v100, v100
	v_exp_f32_e32 v101, v101
	v_exp_f32_e32 v102, v102
	v_exp_f32_e32 v103, v103
	v_exp_f32_e32 v160, v160
	v_exp_f32_e32 v161, v161
	v_exp_f32_e32 v162, v162
	v_exp_f32_e32 v163, v163
	v_min_f32_e32 v108, 0x7149f2ca, v108
	v_min_f32_e32 v109, 0x7149f2ca, v109
	v_min_f32_e32 v110, 0x7149f2ca, v110
	v_min_f32_e32 v111, 0x7149f2ca, v111
	v_min_f32_e32 v104, 0x7149f2ca, v104
	v_min_f32_e32 v105, 0x7149f2ca, v105
	v_min_f32_e32 v106, 0x7149f2ca, v106
	v_min_f32_e32 v107, 0x7149f2ca, v107
	v_min_f32_e32 v100, 0x7149f2ca, v100
	v_min_f32_e32 v101, 0x7149f2ca, v101
	v_min_f32_e32 v102, 0x7149f2ca, v102
	v_min_f32_e32 v103, 0x7149f2ca, v103
	v_add_f32_e32 v108, 1.0, v108
	v_add_f32_e32 v109, 1.0, v109
	v_add_f32_e32 v110, 1.0, v110
	v_add_f32_e32 v111, 1.0, v111
	v_add_f32_e32 v104, 1.0, v104
;     __device__ __forceinline__ void operator()(f32x4 (&acc)[2][2][4][2], const Unit& u, int wr, int wc, int fr, int fq) const {
;     ...
;             for (int ai = 0; ai < 2; ++ai)
; #pragma unroll
;                 for (int m = 0; m < 4; ++m) {
;                     bf16_t* rowp = O + (size_t)(row0q + ai * HALF + m * 16) * LDP + ch;
;                     float r0v[4], r1v[4], g2v[4], szv[4];
; #pragma unroll
;                     for (int j = 0; j < 4; ++j) {
;                         const float ea = fminf(__builtin_amdgcn_exp2f(-1.4426950409f * acc[ai][0][m][0][j]), 1e30f);
;                         const float eb = fminf(__builtin_amdgcn_exp2f(-1.4426950409f * acc[ai][0][m][1][j]), 1e30f);
;                         const float ec = fminf(__builtin_amdgcn_exp2f(-1.4426950409f * acc[ai][1][m][0][j]), 1e30f);
;                         const float xz = acc[ai][1][m][1][j];
;                         const float ia = __builtin_amdgcn_rcpf(1.0f + ea), ib = __builtin_amdgcn_rcpf(1.0f + eb), ic = __builtin_amdgcn_rcpf(1.0f + ec);
;                         r0v[j] = (1.0f + eb) * ia; r1v[j] = (1.0f + ec) * ib; g2v[j] = ic; szv[j] = xz * sigmoid_f(xz);
;                     }
;                     u32x2 wr0, wr1, wg2, wsz;
;                     wr0.x = cvt_pk_bf16(r0v[0], r0v[1]); wr0.y = cvt_pk_bf16(r0v[2], r0v[3]);
;                     wr1.x = cvt_pk_bf16(r1v[0], r1v[1]); wr1.y = cvt_pk_bf16(r1v[2], r1v[3]);
;                     wg2.x = cvt_pk_bf16(g2v[0], g2v[1]); wg2.y = cvt_pk_bf16(g2v[2], g2v[3]);
;                     wsz.x = cvt_pk_bf16(szv[0], szv[1]); wsz.y = cvt_pk_bf16(szv[2], szv[3]);
;                     const bool odd = (fq & 1) != 0;
;                     const u32x2 s0 = odd ? wr0 : wg2, s1 = odd ? wr1 : wsz;
;                     u32x2 q0, q1;
;                     q0.x = (unsigned)__shfl_xor((int)s0.x, 16); q0.y = (unsigned)__shfl_xor((int)s0.y, 16);
;                     q1.x = (unsigned)__shfl_xor((int)s1.x, 16); q1.y = (unsigned)__shfl_xor((int)s1.y, 16);
;                     u32x4 o0, o1;
;                     if (!odd) { o0 = (u32x4){wr0.x, wr0.y, q0.x, q0.y}; o1 = (u32x4){wr1.x, wr1.y, q1.x, q1.y}; }
;                     else      { o0 = (u32x4){q0.x, q0.y, wg2.x, wg2.y}; o1 = (u32x4){q1.x, q1.y, wsz.x, wsz.y}; }
;                     bf16_t* rp8 = rowp - (odd ? 4 : 0);
;                     *(u32x4*)(rp8 + (odd ? S_G2 : S_G0)) = o0;
	v_add_f32_e32 v105, 1.0, v105
	v_add_f32_e32 v106, 1.0, v106
	v_add_f32_e32 v107, 1.0, v107
	v_add_f32_e32 v100, 1.0, v100
	v_add_f32_e32 v101, 1.0, v101
	v_add_f32_e32 v102, 1.0, v102
	v_add_f32_e32 v103, 1.0, v103
	v_add_f32_e32 v160, 1.0, v160
	v_add_f32_e32 v161, 1.0, v161
	v_add_f32_e32 v162, 1.0, v162
	v_add_f32_e32 v163, 1.0, v163
	v_rcp_f32_e32 v152, v108
	v_rcp_f32_e32 v153, v109
	v_rcp_f32_e32 v154, v110
	v_rcp_f32_e32 v155, v111
	v_rcp_f32_e32 v156, v104
	v_rcp_f32_e32 v157, v105
	v_rcp_f32_e32 v158, v106
	v_rcp_f32_e32 v159, v107
	v_rcp_f32_e32 v160, v160
	v_rcp_f32_e32 v161, v161
	v_rcp_f32_e32 v162, v162
	v_rcp_f32_e32 v163, v163
	v_mul_f32_e32 v152, v104, v152
	v_mul_f32_e32 v153, v105, v153
	v_mul_f32_e32 v154, v106, v154
	v_mul_f32_e32 v155, v107, v155
	v_mul_f32_e32 v156, v100, v156
	v_mul_f32_e32 v157, v101, v157
	v_mul_f32_e32 v158, v102, v158
	v_mul_f32_e32 v159, v103, v159
	v_rcp_f32_e32 v100, v100
	v_rcp_f32_e32 v101, v101
	v_rcp_f32_e32 v102, v102
	v_rcp_f32_e32 v103, v103
	v_mul_f32_e32 v160, v96, v160
	v_mul_f32_e32 v161, v97, v161
	v_mul_f32_e32 v162, v98, v162
	v_mul_f32_e32 v163, v99, v163
	v_cvt_pk_bf16_f32 v176, v152, v153
	v_cvt_pk_bf16_f32 v177, v154, v155
	v_cvt_pk_bf16_f32 v180, v156, v157
	v_cvt_pk_bf16_f32 v181, v158, v159
	v_cvt_pk_bf16_f32 v182, v160, v161
	v_cvt_pk_bf16_f32 v183, v162, v163
	v_cvt_pk_bf16_f32 v178, v100, v101
	v_cvt_pk_bf16_f32 v179, v102, v103
	s_nop 1
	v_permlane16_swap_b32_e32 v180, v182
	v_permlane16_swap_b32_e32 v181, v183
	v_permlane16_swap_b32_e32 v176, v178
	v_permlane16_swap_b32_e32 v177, v179
	global_store_dwordx4 v151, v[180:183], s[24:25]
	global_store_dwordx4 v150, v[176:179], s[24:25]
	s_add_u32 s24, s24, 0x8000
	s_addc_u32 s25, s25, 0
	v_mul_f32_e32 v92, 0xbfb8aa3b, v92
	v_mul_f32_e32 v93, 0xbfb8aa3b, v93
	v_mul_f32_e32 v94, 0xbfb8aa3b, v94
	v_mul_f32_e32 v95, 0xbfb8aa3b, v95
	v_mul_f32_e32 v88, 0xbfb8aa3b, v88
	v_mul_f32_e32 v89, 0xbfb8aa3b, v89
	v_mul_f32_e32 v90, 0xbfb8aa3b, v90
	v_mul_f32_e32 v91, 0xbfb8aa3b, v91
	v_mul_f32_e32 v84, 0xbfb8aa3b, v84
	v_mul_f32_e32 v85, 0xbfb8aa3b, v85
	v_mul_f32_e32 v86, 0xbfb8aa3b, v86
	v_mul_f32_e32 v87, 0xbfb8aa3b, v87
	v_mul_f32_e32 v160, 0xbfb8aa3b, v80
	v_mul_f32_e32 v161, 0xbfb8aa3b, v81
	v_mul_f32_e32 v162, 0xbfb8aa3b, v82
	v_mul_f32_e32 v163, 0xbfb8aa3b, v83
	v_exp_f32_e32 v92, v92
	v_exp_f32_e32 v93, v93
	v_exp_f32_e32 v94, v94
	v_exp_f32_e32 v95, v95
	v_exp_f32_e32 v88, v88
	v_exp_f32_e32 v89, v89
	v_exp_f32_e32 v90, v90
	v_exp_f32_e32 v91, v91
	v_exp_f32_e32 v84, v84
	v_exp_f32_e32 v85, v85
	v_exp_f32_e32 v86, v86
	v_exp_f32_e32 v87, v87
	v_exp_f32_e32 v160, v160
	v_exp_f32_e32 v161, v161
	v_exp_f32_e32 v162, v162
	v_exp_f32_e32 v163, v163
	v_min_f32_e32 v92, 0x7149f2ca, v92
	v_min_f32_e32 v93, 0x7149f2ca, v93
	v_min_f32_e32 v94, 0x7149f2ca, v94
	v_min_f32_e32 v95, 0x7149f2ca, v95
	v_min_f32_e32 v88, 0x7149f2ca, v88
	v_min_f32_e32 v89, 0x7149f2ca, v89
	v_min_f32_e32 v90, 0x7149f2ca, v90
	v_min_f32_e32 v91, 0x7149f2ca, v91
	v_min_f32_e32 v84, 0x7149f2ca, v84
	v_min_f32_e32 v85, 0x7149f2ca, v85
	v_min_f32_e32 v86, 0x7149f2ca, v86
	v_min_f32_e32 v87, 0x7149f2ca, v87
	v_add_f32_e32 v92, 1.0, v92
	v_add_f32_e32 v93, 1.0, v93
	v_add_f32_e32 v94, 1.0, v94
	v_add_f32_e32 v95, 1.0, v95
	v_add_f32_e32 v88, 1.0, v88
	v_add_f32_e32 v89, 1.0, v89
	v_add_f32_e32 v90, 1.0, v90
	v_add_f32_e32 v91, 1.0, v91
	v_add_f32_e32 v84, 1.0, v84
	v_add_f32_e32 v85, 1.0, v85
	v_add_f32_e32 v86, 1.0, v86
	v_add_f32_e32 v87, 1.0, v87
	v_add_f32_e32 v160, 1.0, v160
	v_add_f32_e32 v161, 1.0, v161
	v_add_f32_e32 v162, 1.0, v162
	v_add_f32_e32 v163, 1.0, v163
	v_rcp_f32_e32 v152, v92
	v_rcp_f32_e32 v153, v93
	v_rcp_f32_e32 v154, v94
	v_rcp_f32_e32 v155, v95
	v_rcp_f32_e32 v156, v88
	v_rcp_f32_e32 v157, v89
	v_rcp_f32_e32 v158, v90
	v_rcp_f32_e32 v159, v91
	v_rcp_f32_e32 v160, v160
	v_rcp_f32_e32 v161, v161
	v_rcp_f32_e32 v162, v162
	v_rcp_f32_e32 v163, v163
	v_mul_f32_e32 v152, v88, v152
	v_mul_f32_e32 v153, v89, v153
	v_mul_f32_e32 v154, v90, v154
	v_mul_f32_e32 v155, v91, v155
	v_mul_f32_e32 v156, v84, v156
	v_mul_f32_e32 v157, v85, v157
	v_mul_f32_e32 v158, v86, v158
	v_mul_f32_e32 v159, v87, v159
	v_rcp_f32_e32 v84, v84
	v_rcp_f32_e32 v85, v85
	v_rcp_f32_e32 v86, v86
	v_rcp_f32_e32 v87, v87
	v_mul_f32_e32 v160, v80, v160
	v_mul_f32_e32 v161, v81, v161
	v_mul_f32_e32 v162, v82, v162
	v_mul_f32_e32 v163, v83, v163
	v_cvt_pk_bf16_f32 v168, v152, v153
	v_cvt_pk_bf16_f32 v169, v154, v155
	v_cvt_pk_bf16_f32 v172, v156, v157
	v_cvt_pk_bf16_f32 v173, v158, v159
	v_cvt_pk_bf16_f32 v174, v160, v161
	v_cvt_pk_bf16_f32 v175, v162, v163
	v_cvt_pk_bf16_f32 v170, v84, v85
	v_cvt_pk_bf16_f32 v171, v86, v87
	s_nop 1
	v_permlane16_swap_b32_e32 v172, v174
	v_permlane16_swap_b32_e32 v173, v175
	v_permlane16_swap_b32_e32 v168, v170
	v_permlane16_swap_b32_e32 v169, v171
	global_store_dwordx4 v151, v[172:175], s[24:25]
	global_store_dwordx4 v150, v[168:171], s[24:25]
	s_add_u32 s24, s24, 0x8000
	s_addc_u32 s25, s25, 0
	v_mul_f32_e32 v76, 0xbfb8aa3b, v76
	v_mul_f32_e32 v77, 0xbfb8aa3b, v77
	v_mul_f32_e32 v78, 0xbfb8aa3b, v78
	v_mul_f32_e32 v79, 0xbfb8aa3b, v79
	v_mul_f32_e32 v72, 0xbfb8aa3b, v72
	v_mul_f32_e32 v73, 0xbfb8aa3b, v73
	v_mul_f32_e32 v74, 0xbfb8aa3b, v74
	v_mul_f32_e32 v75, 0xbfb8aa3b, v75
	v_mul_f32_e32 v68, 0xbfb8aa3b, v68
	v_mul_f32_e32 v69, 0xbfb8aa3b, v69
	v_mul_f32_e32 v70, 0xbfb8aa3b, v70
	v_mul_f32_e32 v71, 0xbfb8aa3b, v71
	v_mul_f32_e32 v160, 0xbfb8aa3b, v64
	v_mul_f32_e32 v161, 0xbfb8aa3b, v65
	v_mul_f32_e32 v162, 0xbfb8aa3b, v66
	v_mul_f32_e32 v163, 0xbfb8aa3b, v67
	v_exp_f32_e32 v76, v76
	v_exp_f32_e32 v77, v77
	v_exp_f32_e32 v78, v78
;     __device__ __forceinline__ void operator()(f32x4 (&acc)[2][2][4][2], const Unit& u, int wr, int wc, int fr, int fq) const {
;     ...
;             for (int ai = 0; ai < 2; ++ai)
; #pragma unroll
;                 for (int m = 0; m < 4; ++m) {
;                     bf16_t* rowp = O + (size_t)(row0q + ai * HALF + m * 16) * LDP + ch;
;                     float r0v[4], r1v[4], g2v[4], szv[4];
; #pragma unroll
;                     for (int j = 0; j < 4; ++j) {
;                         const float ea = fminf(__builtin_amdgcn_exp2f(-1.4426950409f * acc[ai][0][m][0][j]), 1e30f);
;                         const float eb = fminf(__builtin_amdgcn_exp2f(-1.4426950409f * acc[ai][0][m][1][j]), 1e30f);
;                         const float ec = fminf(__builtin_amdgcn_exp2f(-1.4426950409f * acc[ai][1][m][0][j]), 1e30f);
;                         const float xz = acc[ai][1][m][1][j];
;                         const float ia = __builtin_amdgcn_rcpf(1.0f + ea), ib = __builtin_amdgcn_rcpf(1.0f + eb), ic = __builtin_amdgcn_rcpf(1.0f + ec);
;                         r0v[j] = (1.0f + eb) * ia; r1v[j] = (1.0f + ec) * ib; g2v[j] = ic; szv[j] = xz * sigmoid_f(xz);
;                     }
;                     u32x2 wr0, wr1, wg2, wsz;
;                     wr0.x = cvt_pk_bf16(r0v[0], r0v[1]); wr0.y = cvt_pk_bf16(r0v[2], r0v[3]);
;                     wr1.x = cvt_pk_bf16(r1v[0], r1v[1]); wr1.y = cvt_pk_bf16(r1v[2], r1v[3]);
;                     wg2.x = cvt_pk_bf16(g2v[0], g2v[1]); wg2.y = cvt_pk_bf16(g2v[2], g2v[3]);
;                     wsz.x = cvt_pk_bf16(szv[0], szv[1]); wsz.y = cvt_pk_bf16(szv[2], szv[3]);
;                     const bool odd = (fq & 1) != 0;
;                     const u32x2 s0 = odd ? wr0 : wg2, s1 = odd ? wr1 : wsz;
;                     u32x2 q0, q1;
;                     q0.x = (unsigned)__shfl_xor((int)s0.x, 16); q0.y = (unsigned)__shfl_xor((int)s0.y, 16);
;                     q1.x = (unsigned)__shfl_xor((int)s1.x, 16); q1.y = (unsigned)__shfl_xor((int)s1.y, 16);
;                     u32x4 o0, o1;
;                     if (!odd) { o0 = (u32x4){wr0.x, wr0.y, q0.x, q0.y}; o1 = (u32x4){wr1.x, wr1.y, q1.x, q1.y}; }
;                     else      { o0 = (u32x4){q0.x, q0.y, wg2.x, wg2.y}; o1 = (u32x4){q1.x, q1.y, wsz.x, wsz.y}; }
;                     bf16_t* rp8 = rowp - (odd ? 4 : 0);
;                     *(u32x4*)(rp8 + (odd ? S_G2 : S_G0)) = o0;
	v_exp_f32_e32 v79, v79
	v_exp_f32_e32 v72, v72
	v_exp_f32_e32 v73, v73
	v_exp_f32_e32 v74, v74
	v_exp_f32_e32 v75, v75
	v_exp_f32_e32 v68, v68
	v_exp_f32_e32 v69, v69
	v_exp_f32_e32 v70, v70
	v_exp_f32_e32 v71, v71
	v_exp_f32_e32 v160, v160
	v_exp_f32_e32 v161, v161
	v_exp_f32_e32 v162, v162
	v_exp_f32_e32 v163, v163
	v_min_f32_e32 v76, 0x7149f2ca, v76
	v_min_f32_e32 v77, 0x7149f2ca, v77
	v_min_f32_e32 v78, 0x7149f2ca, v78
	v_min_f32_e32 v79, 0x7149f2ca, v79
	v_min_f32_e32 v72, 0x7149f2ca, v72
	v_min_f32_e32 v73, 0x7149f2ca, v73
	v_min_f32_e32 v74, 0x7149f2ca, v74
	v_min_f32_e32 v75, 0x7149f2ca, v75
	v_min_f32_e32 v68, 0x7149f2ca, v68
	v_min_f32_e32 v69, 0x7149f2ca, v69
	v_min_f32_e32 v70, 0x7149f2ca, v70
	v_min_f32_e32 v71, 0x7149f2ca, v71
	v_add_f32_e32 v76, 1.0, v76
	v_add_f32_e32 v77, 1.0, v77
	v_add_f32_e32 v78, 1.0, v78
	v_add_f32_e32 v79, 1.0, v79
	v_add_f32_e32 v72, 1.0, v72
	v_add_f32_e32 v73, 1.0, v73
	v_add_f32_e32 v74, 1.0, v74
	v_add_f32_e32 v75, 1.0, v75
	v_add_f32_e32 v68, 1.0, v68
	v_add_f32_e32 v69, 1.0, v69
	v_add_f32_e32 v70, 1.0, v70
	v_add_f32_e32 v71, 1.0, v71
	v_add_f32_e32 v160, 1.0, v160
	v_add_f32_e32 v161, 1.0, v161
	v_add_f32_e32 v162, 1.0, v162
	v_add_f32_e32 v163, 1.0, v163
	v_rcp_f32_e32 v152, v76
	v_rcp_f32_e32 v153, v77
	v_rcp_f32_e32 v154, v78
	v_rcp_f32_e32 v155, v79
	v_rcp_f32_e32 v156, v72
	v_rcp_f32_e32 v157, v73
	v_rcp_f32_e32 v158, v74
	v_rcp_f32_e32 v159, v75
	v_rcp_f32_e32 v160, v160
	v_rcp_f32_e32 v161, v161
	v_rcp_f32_e32 v162, v162
	v_rcp_f32_e32 v163, v163
	v_mul_f32_e32 v152, v72, v152
	v_mul_f32_e32 v153, v73, v153
	v_mul_f32_e32 v154, v74, v154
	v_mul_f32_e32 v155, v75, v155
	v_mul_f32_e32 v156, v68, v156
	v_mul_f32_e32 v157, v69, v157
	v_mul_f32_e32 v158, v70, v158
	v_mul_f32_e32 v159, v71, v159
	v_rcp_f32_e32 v68, v68
	v_rcp_f32_e32 v69, v69
	v_rcp_f32_e32 v70, v70
	v_rcp_f32_e32 v71, v71
	v_mul_f32_e32 v160, v64, v160
	v_mul_f32_e32 v161, v65, v161
	v_mul_f32_e32 v162, v66, v162
	v_mul_f32_e32 v163, v67, v163
	v_cvt_pk_bf16_f32 v176, v152, v153
	v_cvt_pk_bf16_f32 v177, v154, v155
	v_cvt_pk_bf16_f32 v180, v156, v157
	v_cvt_pk_bf16_f32 v181, v158, v159
	v_cvt_pk_bf16_f32 v182, v160, v161
	v_cvt_pk_bf16_f32 v183, v162, v163
	v_cvt_pk_bf16_f32 v178, v68, v69
	v_cvt_pk_bf16_f32 v179, v70, v71
	s_nop 1
	v_permlane16_swap_b32_e32 v180, v182
	v_permlane16_swap_b32_e32 v181, v183
	v_permlane16_swap_b32_e32 v176, v178
	v_permlane16_swap_b32_e32 v177, v179
	global_store_dwordx4 v151, v[180:183], s[24:25]
	global_store_dwordx4 v150, v[176:179], s[24:25]
	s_add_u32 s24, s24, 0x28000
	s_addc_u32 s25, s25, 0
	v_mul_f32_e32 v60, 0xbfb8aa3b, v60
	v_mul_f32_e32 v61, 0xbfb8aa3b, v61
	v_mul_f32_e32 v62, 0xbfb8aa3b, v62
	v_mul_f32_e32 v63, 0xbfb8aa3b, v63
	v_mul_f32_e32 v56, 0xbfb8aa3b, v56
	v_mul_f32_e32 v57, 0xbfb8aa3b, v57
	v_mul_f32_e32 v58, 0xbfb8aa3b, v58
	v_mul_f32_e32 v59, 0xbfb8aa3b, v59
	v_mul_f32_e32 v52, 0xbfb8aa3b, v52
	v_mul_f32_e32 v53, 0xbfb8aa3b, v53
	v_mul_f32_e32 v54, 0xbfb8aa3b, v54
	v_mul_f32_e32 v55, 0xbfb8aa3b, v55
	v_mul_f32_e32 v160, 0xbfb8aa3b, v48
	v_mul_f32_e32 v161, 0xbfb8aa3b, v49
	v_mul_f32_e32 v162, 0xbfb8aa3b, v50
	v_mul_f32_e32 v163, 0xbfb8aa3b, v51
	v_exp_f32_e32 v60, v60
	v_exp_f32_e32 v61, v61
	v_exp_f32_e32 v62, v62
	v_exp_f32_e32 v63, v63
	v_exp_f32_e32 v56, v56
	v_exp_f32_e32 v57, v57
	v_exp_f32_e32 v58, v58
	v_exp_f32_e32 v59, v59
	v_exp_f32_e32 v52, v52
	v_exp_f32_e32 v53, v53
	v_exp_f32_e32 v54, v54
	v_exp_f32_e32 v55, v55
	v_exp_f32_e32 v160, v160
	v_exp_f32_e32 v161, v161
	v_exp_f32_e32 v162, v162
	v_exp_f32_e32 v163, v163
	v_min_f32_e32 v60, 0x7149f2ca, v60
	v_min_f32_e32 v61, 0x7149f2ca, v61
	v_min_f32_e32 v62, 0x7149f2ca, v62
	v_min_f32_e32 v63, 0x7149f2ca, v63
	v_min_f32_e32 v56, 0x7149f2ca, v56
	v_min_f32_e32 v57, 0x7149f2ca, v57
	v_min_f32_e32 v58, 0x7149f2ca, v58
	v_min_f32_e32 v59, 0x7149f2ca, v59
	v_min_f32_e32 v52, 0x7149f2ca, v52
	v_min_f32_e32 v53, 0x7149f2ca, v53
	v_min_f32_e32 v54, 0x7149f2ca, v54
	v_min_f32_e32 v55, 0x7149f2ca, v55
	v_add_f32_e32 v60, 1.0, v60
	v_add_f32_e32 v61, 1.0, v61
	v_add_f32_e32 v62, 1.0, v62
	v_add_f32_e32 v63, 1.0, v63
	v_add_f32_e32 v56, 1.0, v56
	v_add_f32_e32 v57, 1.0, v57
	v_add_f32_e32 v58, 1.0, v58
	v_add_f32_e32 v59, 1.0, v59
	v_add_f32_e32 v52, 1.0, v52
	v_add_f32_e32 v53, 1.0, v53
	v_add_f32_e32 v54, 1.0, v54
	v_add_f32_e32 v55, 1.0, v55
	v_add_f32_e32 v160, 1.0, v160
	v_add_f32_e32 v161, 1.0, v161
	v_add_f32_e32 v162, 1.0, v162
	v_add_f32_e32 v163, 1.0, v163
	v_rcp_f32_e32 v152, v60
	v_rcp_f32_e32 v153, v61
	v_rcp_f32_e32 v154, v62
	v_rcp_f32_e32 v155, v63
	v_rcp_f32_e32 v156, v56
	v_rcp_f32_e32 v157, v57
	v_rcp_f32_e32 v158, v58
	v_rcp_f32_e32 v159, v59
	v_rcp_f32_e32 v160, v160
	v_rcp_f32_e32 v161, v161
	v_rcp_f32_e32 v162, v162
	v_rcp_f32_e32 v163, v163
	v_mul_f32_e32 v152, v56, v152
	v_mul_f32_e32 v153, v57, v153
	v_mul_f32_e32 v154, v58, v154
	v_mul_f32_e32 v155, v59, v155
	v_mul_f32_e32 v156, v52, v156
	v_mul_f32_e32 v157, v53, v157
	v_mul_f32_e32 v158, v54, v158
	v_mul_f32_e32 v159, v55, v159
	v_rcp_f32_e32 v52, v52
	v_rcp_f32_e32 v53, v53
	v_rcp_f32_e32 v54, v54
	v_rcp_f32_e32 v55, v55
	v_mul_f32_e32 v160, v48, v160
	v_mul_f32_e32 v161, v49, v161
	v_mul_f32_e32 v162, v50, v162
	v_mul_f32_e32 v163, v51, v163
	v_cvt_pk_bf16_f32 v168, v152, v153
	v_cvt_pk_bf16_f32 v169, v154, v155
	v_cvt_pk_bf16_f32 v172, v156, v157
	v_cvt_pk_bf16_f32 v173, v158, v159
	v_cvt_pk_bf16_f32 v174, v160, v161
	v_cvt_pk_bf16_f32 v175, v162, v163
	v_cvt_pk_bf16_f32 v170, v52, v53
	v_cvt_pk_bf16_f32 v171, v54, v55
	s_nop 1
	v_permlane16_swap_b32_e32 v172, v174
	v_permlane16_swap_b32_e32 v173, v175
	v_permlane16_swap_b32_e32 v168, v170
; __device__ __forceinline__ unsigned cvt_pk_bf16(float lo, float hi) { unsigned r; asm volatile("v_cvt_pk_bf16_f32 %0, %1, %2" : "=v"(r) : "v"(lo), "v"(hi)); return r; }
;     __device__ __forceinline__ void operator()(f32x4 (&acc)[2][2][4][2], const Unit& u, int wr, int wc, int fr, int fq) const {
;     ...
;                         const float ea = fminf(__builtin_amdgcn_exp2f(-1.4426950409f * acc[ai][0][m][0][j]), 1e30f);
;                         const float eb = fminf(__builtin_amdgcn_exp2f(-1.4426950409f * acc[ai][0][m][1][j]), 1e30f);
;                         const float ec = fminf(__builtin_amdgcn_exp2f(-1.4426950409f * acc[ai][1][m][0][j]), 1e30f);
;                         const float xz = acc[ai][1][m][1][j];
;                         const float ia = __builtin_amdgcn_rcpf(1.0f + ea), ib = __builtin_amdgcn_rcpf(1.0f + eb), ic = __builtin_amdgcn_rcpf(1.0f + ec);
;                         r0v[j] = (1.0f + eb) * ia; r1v[j] = (1.0f + ec) * ib; g2v[j] = ic; szv[j] = xz * sigmoid_f(xz);
;                     }
;                     u32x2 wr0, wr1, wg2, wsz;
;                     wr0.x = cvt_pk_bf16(r0v[0], r0v[1]); wr0.y = cvt_pk_bf16(r0v[2], r0v[3]);
;                     wr1.x = cvt_pk_bf16(r1v[0], r1v[1]); wr1.y = cvt_pk_bf16(r1v[2], r1v[3]);
;                     wg2.x = cvt_pk_bf16(g2v[0], g2v[1]); wg2.y = cvt_pk_bf16(g2v[2], g2v[3]);
;                     wsz.x = cvt_pk_bf16(szv[0], szv[1]); wsz.y = cvt_pk_bf16(szv[2], szv[3]);
;                     const bool odd = (fq & 1) != 0;
;                     const u32x2 s0 = odd ? wr0 : wg2, s1 = odd ? wr1 : wsz;
;                     u32x2 q0, q1;
;                     q0.x = (unsigned)__shfl_xor((int)s0.x, 16); q0.y = (unsigned)__shfl_xor((int)s0.y, 16);
;                     q1.x = (unsigned)__shfl_xor((int)s1.x, 16); q1.y = (unsigned)__shfl_xor((int)s1.y, 16);
;                     u32x4 o0, o1;
;                     if (!odd) { o0 = (u32x4){wr0.x, wr0.y, q0.x, q0.y}; o1 = (u32x4){wr1.x, wr1.y, q1.x, q1.y}; }
;                     else      { o0 = (u32x4){q0.x, q0.y, wg2.x, wg2.y}; o1 = (u32x4){q1.x, q1.y, wsz.x, wsz.y}; }
;                     bf16_t* rp8 = rowp - (odd ? 4 : 0);
;                     *(u32x4*)(rp8 + (odd ? S_G2 : S_G0)) = o0;
;                     *(u32x4*)(rp8 + (odd ? S_BZ : S_G1)) = o1;
	v_permlane16_swap_b32_e32 v169, v171
	global_store_dwordx4 v151, v[172:175], s[24:25]
	global_store_dwordx4 v150, v[168:171], s[24:25]
	s_add_u32 s24, s24, 0x8000
	s_addc_u32 s25, s25, 0
	v_mul_f32_e32 v44, 0xbfb8aa3b, v44
	v_mul_f32_e32 v45, 0xbfb8aa3b, v45
	v_mul_f32_e32 v46, 0xbfb8aa3b, v46
	v_mul_f32_e32 v47, 0xbfb8aa3b, v47
	v_mul_f32_e32 v40, 0xbfb8aa3b, v40
	v_mul_f32_e32 v41, 0xbfb8aa3b, v41
	v_mul_f32_e32 v42, 0xbfb8aa3b, v42
	v_mul_f32_e32 v43, 0xbfb8aa3b, v43
	v_mul_f32_e32 v36, 0xbfb8aa3b, v36
	v_mul_f32_e32 v37, 0xbfb8aa3b, v37
	v_mul_f32_e32 v38, 0xbfb8aa3b, v38
	v_mul_f32_e32 v39, 0xbfb8aa3b, v39
	v_mul_f32_e32 v160, 0xbfb8aa3b, v32
	v_mul_f32_e32 v161, 0xbfb8aa3b, v33
	v_mul_f32_e32 v162, 0xbfb8aa3b, v34
	v_mul_f32_e32 v163, 0xbfb8aa3b, v35
	v_exp_f32_e32 v44, v44
	v_exp_f32_e32 v45, v45
	v_exp_f32_e32 v46, v46
	v_exp_f32_e32 v47, v47
	v_exp_f32_e32 v40, v40
	v_exp_f32_e32 v41, v41
	v_exp_f32_e32 v42, v42
	v_exp_f32_e32 v43, v43
	v_exp_f32_e32 v36, v36
	v_exp_f32_e32 v37, v37
	v_exp_f32_e32 v38, v38
	v_exp_f32_e32 v39, v39
	v_exp_f32_e32 v160, v160
	v_exp_f32_e32 v161, v161
	v_exp_f32_e32 v162, v162
	v_exp_f32_e32 v163, v163
	v_min_f32_e32 v44, 0x7149f2ca, v44
	v_min_f32_e32 v45, 0x7149f2ca, v45
	v_min_f32_e32 v46, 0x7149f2ca, v46
	v_min_f32_e32 v47, 0x7149f2ca, v47
	v_min_f32_e32 v40, 0x7149f2ca, v40
	v_min_f32_e32 v41, 0x7149f2ca, v41
	v_min_f32_e32 v42, 0x7149f2ca, v42
	v_min_f32_e32 v43, 0x7149f2ca, v43
	v_min_f32_e32 v36, 0x7149f2ca, v36
	v_min_f32_e32 v37, 0x7149f2ca, v37
	v_min_f32_e32 v38, 0x7149f2ca, v38
	v_min_f32_e32 v39, 0x7149f2ca, v39
	v_add_f32_e32 v44, 1.0, v44
	v_add_f32_e32 v45, 1.0, v45
	v_add_f32_e32 v46, 1.0, v46
	v_add_f32_e32 v47, 1.0, v47
	v_add_f32_e32 v40, 1.0, v40
	v_add_f32_e32 v41, 1.0, v41
	v_add_f32_e32 v42, 1.0, v42
	v_add_f32_e32 v43, 1.0, v43
	v_add_f32_e32 v36, 1.0, v36
	v_add_f32_e32 v37, 1.0, v37
	v_add_f32_e32 v38, 1.0, v38
	v_add_f32_e32 v39, 1.0, v39
	v_add_f32_e32 v160, 1.0, v160
	v_add_f32_e32 v161, 1.0, v161
	v_add_f32_e32 v162, 1.0, v162
	v_add_f32_e32 v163, 1.0, v163
	v_rcp_f32_e32 v152, v44
	v_rcp_f32_e32 v153, v45
	v_rcp_f32_e32 v154, v46
	v_rcp_f32_e32 v155, v47
	v_rcp_f32_e32 v156, v40
	v_rcp_f32_e32 v157, v41
	v_rcp_f32_e32 v158, v42
	v_rcp_f32_e32 v159, v43
	v_rcp_f32_e32 v160, v160
	v_rcp_f32_e32 v161, v161
	v_rcp_f32_e32 v162, v162
	v_rcp_f32_e32 v163, v163
	v_mul_f32_e32 v152, v40, v152
	v_mul_f32_e32 v153, v41, v153
	v_mul_f32_e32 v154, v42, v154
	v_mul_f32_e32 v155, v43, v155
	v_mul_f32_e32 v156, v36, v156
	v_mul_f32_e32 v157, v37, v157
	v_mul_f32_e32 v158, v38, v158
	v_mul_f32_e32 v159, v39, v159
	v_rcp_f32_e32 v36, v36
	v_rcp_f32_e32 v37, v37
	v_rcp_f32_e32 v38, v38
	v_rcp_f32_e32 v39, v39
	v_mul_f32_e32 v160, v32, v160
	v_mul_f32_e32 v161, v33, v161
	v_mul_f32_e32 v162, v34, v162
	v_mul_f32_e32 v163, v35, v163
	v_cvt_pk_bf16_f32 v176, v152, v153
	v_cvt_pk_bf16_f32 v177, v154, v155
	v_cvt_pk_bf16_f32 v180, v156, v157
	v_cvt_pk_bf16_f32 v181, v158, v159
	v_cvt_pk_bf16_f32 v182, v160, v161
	v_cvt_pk_bf16_f32 v183, v162, v163
	v_cvt_pk_bf16_f32 v178, v36, v37
	v_cvt_pk_bf16_f32 v179, v38, v39
	s_nop 1
	v_permlane16_swap_b32_e32 v180, v182
	v_permlane16_swap_b32_e32 v181, v183
	v_permlane16_swap_b32_e32 v176, v178
	v_permlane16_swap_b32_e32 v177, v179
	global_store_dwordx4 v151, v[180:183], s[24:25]
	global_store_dwordx4 v150, v[176:179], s[24:25]
	s_add_u32 s24, s24, 0x8000
	s_addc_u32 s25, s25, 0
	v_mul_f32_e32 v28, 0xbfb8aa3b, v28
	v_mul_f32_e32 v29, 0xbfb8aa3b, v29
	v_mul_f32_e32 v30, 0xbfb8aa3b, v30
	v_mul_f32_e32 v31, 0xbfb8aa3b, v31
	v_mul_f32_e32 v24, 0xbfb8aa3b, v24
	v_mul_f32_e32 v25, 0xbfb8aa3b, v25
	v_mul_f32_e32 v26, 0xbfb8aa3b, v26
	v_mul_f32_e32 v27, 0xbfb8aa3b, v27
	v_mul_f32_e32 v20, 0xbfb8aa3b, v20
	v_mul_f32_e32 v21, 0xbfb8aa3b, v21
	v_mul_f32_e32 v22, 0xbfb8aa3b, v22
	v_mul_f32_e32 v23, 0xbfb8aa3b, v23
	v_mul_f32_e32 v160, 0xbfb8aa3b, v16
	v_mul_f32_e32 v161, 0xbfb8aa3b, v17
	v_mul_f32_e32 v162, 0xbfb8aa3b, v18
	v_mul_f32_e32 v163, 0xbfb8aa3b, v19
	v_exp_f32_e32 v28, v28
	v_exp_f32_e32 v29, v29
	v_exp_f32_e32 v30, v30
	v_exp_f32_e32 v31, v31
	v_exp_f32_e32 v24, v24
	v_exp_f32_e32 v25, v25
	v_exp_f32_e32 v26, v26
	v_exp_f32_e32 v27, v27
	v_exp_f32_e32 v20, v20
	v_exp_f32_e32 v21, v21
	v_exp_f32_e32 v22, v22
	v_exp_f32_e32 v23, v23
	v_exp_f32_e32 v160, v160
	v_exp_f32_e32 v161, v161
	v_exp_f32_e32 v162, v162
	v_exp_f32_e32 v163, v163
	v_min_f32_e32 v28, 0x7149f2ca, v28
	v_min_f32_e32 v29, 0x7149f2ca, v29
	v_min_f32_e32 v30, 0x7149f2ca, v30
	v_min_f32_e32 v31, 0x7149f2ca, v31
	v_min_f32_e32 v24, 0x7149f2ca, v24
	v_min_f32_e32 v25, 0x7149f2ca, v25
	v_min_f32_e32 v26, 0x7149f2ca, v26
	v_min_f32_e32 v27, 0x7149f2ca, v27
	v_min_f32_e32 v20, 0x7149f2ca, v20
	v_min_f32_e32 v21, 0x7149f2ca, v21
	v_min_f32_e32 v22, 0x7149f2ca, v22
	v_min_f32_e32 v23, 0x7149f2ca, v23
	v_add_f32_e32 v28, 1.0, v28
	v_add_f32_e32 v29, 1.0, v29
; __device__ __forceinline__ unsigned cvt_pk_bf16(float lo, float hi) { unsigned r; asm volatile("v_cvt_pk_bf16_f32 %0, %1, %2" : "=v"(r) : "v"(lo), "v"(hi)); return r; }
;     __device__ __forceinline__ void operator()(f32x4 (&acc)[2][2][4][2], const Unit& u, int wr, int wc, int fr, int fq) const {
;     ...
;                         const float ea = fminf(__builtin_amdgcn_exp2f(-1.4426950409f * acc[ai][0][m][0][j]), 1e30f);
;                         const float eb = fminf(__builtin_amdgcn_exp2f(-1.4426950409f * acc[ai][0][m][1][j]), 1e30f);
;                         const float ec = fminf(__builtin_amdgcn_exp2f(-1.4426950409f * acc[ai][1][m][0][j]), 1e30f);
;                         const float xz = acc[ai][1][m][1][j];
;                         const float ia = __builtin_amdgcn_rcpf(1.0f + ea), ib = __builtin_amdgcn_rcpf(1.0f + eb), ic = __builtin_amdgcn_rcpf(1.0f + ec);
;                         r0v[j] = (1.0f + eb) * ia; r1v[j] = (1.0f + ec) * ib; g2v[j] = ic; szv[j] = xz * sigmoid_f(xz);
;                     }
;                     u32x2 wr0, wr1, wg2, wsz;
;                     wr0.x = cvt_pk_bf16(r0v[0], r0v[1]); wr0.y = cvt_pk_bf16(r0v[2], r0v[3]);
;                     wr1.x = cvt_pk_bf16(r1v[0], r1v[1]); wr1.y = cvt_pk_bf16(r1v[2], r1v[3]);
;                     wg2.x = cvt_pk_bf16(g2v[0], g2v[1]); wg2.y = cvt_pk_bf16(g2v[2], g2v[3]);
;                     wsz.x = cvt_pk_bf16(szv[0], szv[1]); wsz.y = cvt_pk_bf16(szv[2], szv[3]);
;                     const bool odd = (fq & 1) != 0;
;                     const u32x2 s0 = odd ? wr0 : wg2, s1 = odd ? wr1 : wsz;
;                     u32x2 q0, q1;
;                     q0.x = (unsigned)__shfl_xor((int)s0.x, 16); q0.y = (unsigned)__shfl_xor((int)s0.y, 16);
;                     q1.x = (unsigned)__shfl_xor((int)s1.x, 16); q1.y = (unsigned)__shfl_xor((int)s1.y, 16);
;                     u32x4 o0, o1;
;                     if (!odd) { o0 = (u32x4){wr0.x, wr0.y, q0.x, q0.y}; o1 = (u32x4){wr1.x, wr1.y, q1.x, q1.y}; }
;                     else      { o0 = (u32x4){q0.x, q0.y, wg2.x, wg2.y}; o1 = (u32x4){q1.x, q1.y, wsz.x, wsz.y}; }
;                     bf16_t* rp8 = rowp - (odd ? 4 : 0);
;                     *(u32x4*)(rp8 + (odd ? S_G2 : S_G0)) = o0;
;                     *(u32x4*)(rp8 + (odd ? S_BZ : S_G1)) = o1;
;                 }
;             return;
	v_add_f32_e32 v30, 1.0, v30
	v_add_f32_e32 v31, 1.0, v31
	v_add_f32_e32 v24, 1.0, v24
	v_add_f32_e32 v25, 1.0, v25
	v_add_f32_e32 v26, 1.0, v26
	v_add_f32_e32 v27, 1.0, v27
	v_add_f32_e32 v20, 1.0, v20
	v_add_f32_e32 v21, 1.0, v21
	v_add_f32_e32 v22, 1.0, v22
	v_add_f32_e32 v23, 1.0, v23
	v_add_f32_e32 v160, 1.0, v160
	v_add_f32_e32 v161, 1.0, v161
	v_add_f32_e32 v162, 1.0, v162
	v_add_f32_e32 v163, 1.0, v163
	v_rcp_f32_e32 v152, v28
	v_rcp_f32_e32 v153, v29
	v_rcp_f32_e32 v154, v30
	v_rcp_f32_e32 v155, v31
	v_rcp_f32_e32 v156, v24
	v_rcp_f32_e32 v157, v25
	v_rcp_f32_e32 v158, v26
	v_rcp_f32_e32 v159, v27
	v_rcp_f32_e32 v160, v160
	v_rcp_f32_e32 v161, v161
	v_rcp_f32_e32 v162, v162
	v_rcp_f32_e32 v163, v163
	v_mul_f32_e32 v152, v24, v152
	v_mul_f32_e32 v153, v25, v153
	v_mul_f32_e32 v154, v26, v154
	v_mul_f32_e32 v155, v27, v155
	v_mul_f32_e32 v156, v20, v156
	v_mul_f32_e32 v157, v21, v157
	v_mul_f32_e32 v158, v22, v158
	v_mul_f32_e32 v159, v23, v159
	v_rcp_f32_e32 v20, v20
	v_rcp_f32_e32 v21, v21
	v_rcp_f32_e32 v22, v22
	v_rcp_f32_e32 v23, v23
	v_mul_f32_e32 v160, v16, v160
	v_mul_f32_e32 v161, v17, v161
	v_mul_f32_e32 v162, v18, v162
	v_mul_f32_e32 v163, v19, v163
	v_cvt_pk_bf16_f32 v168, v152, v153
	v_cvt_pk_bf16_f32 v169, v154, v155
	v_cvt_pk_bf16_f32 v172, v156, v157
	v_cvt_pk_bf16_f32 v173, v158, v159
	v_cvt_pk_bf16_f32 v174, v160, v161
	v_cvt_pk_bf16_f32 v175, v162, v163
	v_cvt_pk_bf16_f32 v170, v20, v21
	v_cvt_pk_bf16_f32 v171, v22, v23
	s_nop 1
	v_permlane16_swap_b32_e32 v172, v174
	v_permlane16_swap_b32_e32 v173, v175
	v_permlane16_swap_b32_e32 v168, v170
	v_permlane16_swap_b32_e32 v169, v171
	global_store_dwordx4 v151, v[172:175], s[24:25]
	global_store_dwordx4 v150, v[168:171], s[24:25]
	s_add_u32 s24, s24, 0x8000
	s_addc_u32 s25, s25, 0
	v_mul_f32_e32 v12, 0xbfb8aa3b, v12
	v_mul_f32_e32 v13, 0xbfb8aa3b, v13
	v_mul_f32_e32 v14, 0xbfb8aa3b, v14
	v_mul_f32_e32 v15, 0xbfb8aa3b, v15
	v_mul_f32_e32 v8, 0xbfb8aa3b, v8
	v_mul_f32_e32 v9, 0xbfb8aa3b, v9
	v_mul_f32_e32 v10, 0xbfb8aa3b, v10
	v_mul_f32_e32 v11, 0xbfb8aa3b, v11
	v_mul_f32_e32 v4, 0xbfb8aa3b, v4
	v_mul_f32_e32 v5, 0xbfb8aa3b, v5
	v_mul_f32_e32 v6, 0xbfb8aa3b, v6
	v_mul_f32_e32 v7, 0xbfb8aa3b, v7
	v_mul_f32_e32 v160, 0xbfb8aa3b, v0
	v_mul_f32_e32 v161, 0xbfb8aa3b, v1
	v_mul_f32_e32 v162, 0xbfb8aa3b, v2
	v_mul_f32_e32 v163, 0xbfb8aa3b, v3
	v_exp_f32_e32 v12, v12
	v_exp_f32_e32 v13, v13
	v_exp_f32_e32 v14, v14
	v_exp_f32_e32 v15, v15
	v_exp_f32_e32 v8, v8
	v_exp_f32_e32 v9, v9
	v_exp_f32_e32 v10, v10
	v_exp_f32_e32 v11, v11
	v_exp_f32_e32 v4, v4
	v_exp_f32_e32 v5, v5
	v_exp_f32_e32 v6, v6
	v_exp_f32_e32 v7, v7
	v_exp_f32_e32 v160, v160
	v_exp_f32_e32 v161, v161
	v_exp_f32_e32 v162, v162
	v_exp_f32_e32 v163, v163
	v_min_f32_e32 v12, 0x7149f2ca, v12
	v_min_f32_e32 v13, 0x7149f2ca, v13
	v_min_f32_e32 v14, 0x7149f2ca, v14
	v_min_f32_e32 v15, 0x7149f2ca, v15
	v_min_f32_e32 v8, 0x7149f2ca, v8
	v_min_f32_e32 v9, 0x7149f2ca, v9
	v_min_f32_e32 v10, 0x7149f2ca, v10
	v_min_f32_e32 v11, 0x7149f2ca, v11
	v_min_f32_e32 v4, 0x7149f2ca, v4
	v_min_f32_e32 v5, 0x7149f2ca, v5
	v_min_f32_e32 v6, 0x7149f2ca, v6
	v_min_f32_e32 v7, 0x7149f2ca, v7
	v_add_f32_e32 v12, 1.0, v12
	v_add_f32_e32 v13, 1.0, v13
	v_add_f32_e32 v14, 1.0, v14
	v_add_f32_e32 v15, 1.0, v15
	v_add_f32_e32 v8, 1.0, v8
	v_add_f32_e32 v9, 1.0, v9
	v_add_f32_e32 v10, 1.0, v10
	v_add_f32_e32 v11, 1.0, v11
	v_add_f32_e32 v4, 1.0, v4
	v_add_f32_e32 v5, 1.0, v5
	v_add_f32_e32 v6, 1.0, v6
	v_add_f32_e32 v7, 1.0, v7
	v_add_f32_e32 v160, 1.0, v160
	v_add_f32_e32 v161, 1.0, v161
	v_add_f32_e32 v162, 1.0, v162
	v_add_f32_e32 v163, 1.0, v163
	v_rcp_f32_e32 v152, v12
	v_rcp_f32_e32 v153, v13
	v_rcp_f32_e32 v154, v14
	v_rcp_f32_e32 v155, v15
	v_rcp_f32_e32 v156, v8
	v_rcp_f32_e32 v157, v9
	v_rcp_f32_e32 v158, v10
	v_rcp_f32_e32 v159, v11
	v_rcp_f32_e32 v160, v160
	v_rcp_f32_e32 v161, v161
	v_rcp_f32_e32 v162, v162
	v_rcp_f32_e32 v163, v163
	v_mul_f32_e32 v152, v8, v152
	v_mul_f32_e32 v153, v9, v153
	v_mul_f32_e32 v154, v10, v154
	v_mul_f32_e32 v155, v11, v155
	v_mul_f32_e32 v156, v4, v156
	v_mul_f32_e32 v157, v5, v157
	v_mul_f32_e32 v158, v6, v158
	v_mul_f32_e32 v159, v7, v159
	v_rcp_f32_e32 v4, v4
	v_rcp_f32_e32 v5, v5
	v_rcp_f32_e32 v6, v6
	v_rcp_f32_e32 v7, v7
	v_mul_f32_e32 v160, v0, v160
	v_mul_f32_e32 v161, v1, v161
	v_mul_f32_e32 v162, v2, v162
	v_mul_f32_e32 v163, v3, v163
	v_cvt_pk_bf16_f32 v176, v152, v153
	v_cvt_pk_bf16_f32 v177, v154, v155
	v_cvt_pk_bf16_f32 v180, v156, v157
	v_cvt_pk_bf16_f32 v181, v158, v159
	v_cvt_pk_bf16_f32 v182, v160, v161
	v_cvt_pk_bf16_f32 v183, v162, v163
	v_cvt_pk_bf16_f32 v178, v4, v5
	v_cvt_pk_bf16_f32 v179, v6, v7
	s_nop 1
	v_permlane16_swap_b32_e32 v180, v182
	v_permlane16_swap_b32_e32 v181, v183
	v_permlane16_swap_b32_e32 v176, v178
	v_permlane16_swap_b32_e32 v177, v179
	global_store_dwordx4 v151, v[180:183], s[24:25]
	global_store_dwordx4 v150, v[176:179], s[24:25]
	s_branch .LBB0_298
